# rms(x) rebalance deepened: SSM workgroups do 2 of 8 row pairs, every other wave takes two extra
# speedup vs baseline: 1.0048x; 1.0048x over previous
; __device__ __forceinline__ void rms_row2_bf16(const float* x0, const float* x1, const float* gain, bf16_t* o0, bf16_t* o1, int lane) {
;     const f32x4* xa = (const f32x4*)x0 + lane; const f32x4* xb = (const f32x4*)x1 + lane; const f32x4* gr = (const f32x4*)gain + lane;
;     f32x4 va[8], vb[8]; float sa = 0.f, sb = 0.f;
; #pragma unroll
;     for (int j = 0; j < 8; ++j) va[j] = xa[64 * j];
; #pragma unroll
;     for (int j = 0; j < 8; ++j) vb[j] = xb[64 * j];
; #pragma unroll
;     for (int j = 0; j < 8; ++j) { sa += (va[j][0] * va[j][0] + va[j][1] * va[j][1]) + (va[j][2] * va[j][2] + va[j][3] * va[j][3]); sb += (vb[j][0] * vb[j][0] + vb[j][1] * vb[j][1]) + (vb[j][2] * vb[j][2] + vb[j][3] * vb[j][3]); }
; __global__ void __launch_bounds__(512, 2) fwd_mega(Args a) {
;     ...
;         for (int m = gw; m < MT; m += 2 * NGW) rms_row2_bf16(a.in[I_X] + (size_t)m * DM, a.in[I_X] + (size_t)(m + NGW) * DM, a.in[I_F1N], U + (size_t)m * DM, U + (size_t)(m + NGW) * DM, lane);
.LBB0_219:
	s_or_b64 exec, exec, s[0:1]
	s_add_u32 s74, s92, 0xca00000
	s_addc_u32 s75, s93, 0
	s_cmp_lt_i32 s96, 0x8000
	s_cselect_b64 s[0:1], -1, 0
	s_mov_b32 s51, s2
	v_writelane_b32 v251, s0, 36
	s_movk_i32 s5, 0x7fff
	s_cmpk_gt_i32 s96, 0x7fff
	v_lshlrev_b32_e32 v206, 4, v228
	v_mbcnt_lo_u32_b32 v205, -1, 0
	v_writelane_b32 v251, s1, 37
	s_cbranch_scc1 .LBB0_222
	v_mbcnt_hi_u32_b32 v2, -1, v205
	v_and_b32_e32 v1, 64, v2
	v_add_u32_e32 v3, 64, v1
	v_xor_b32_e32 v1, 1, v2
	v_cmp_lt_i32_e32 vcc, v1, v3
	v_xor_b32_e32 v4, 2, v2
	v_mov_b32_e32 v207, 0
	v_cndmask_b32_e32 v1, v2, v1, vcc
	v_cmp_lt_i32_e32 vcc, v4, v3
	s_waitcnt lgkmcnt(0)
	v_lshl_add_u64 v[68:69], s[16:17], 0, v[206:207]
	s_mov_b64 s[0:1], 0x1000
	v_cndmask_b32_e32 v4, v2, v4, vcc
	v_lshlrev_b32_e32 v81, 2, v4
	v_xor_b32_e32 v4, 4, v2
	v_cmp_lt_i32_e32 vcc, v4, v3
	v_lshl_add_u64 v[72:73], v[68:69], 0, s[0:1]
	s_mov_b64 s[0:1], 0x1400
	v_cndmask_b32_e32 v4, v2, v4, vcc
	v_lshlrev_b32_e32 v87, 2, v4
	v_xor_b32_e32 v4, 8, v2
	v_cmp_lt_i32_e32 vcc, v4, v3
	v_lshl_add_u64 v[74:75], v[68:69], 0, s[0:1]
	s_mov_b64 s[0:1], 0x1800
	v_cndmask_b32_e32 v4, v2, v4, vcc
	v_lshlrev_b32_e32 v89, 2, v4
	v_xor_b32_e32 v4, 16, v2
	v_cmp_lt_i32_e32 vcc, v4, v3
	v_lshl_add_u64 v[76:77], v[68:69], 0, s[0:1]
	s_mov_b64 s[0:1], 0x1c00
	v_cndmask_b32_e32 v4, v2, v4, vcc
	v_lshlrev_b32_e32 v90, 2, v4
	v_xor_b32_e32 v4, 32, v2
	v_cmp_lt_i32_e32 vcc, v4, v3
	v_mov_b32_e32 v3, v207
	v_lshl_add_u64 v[66:67], s[12:13], 0, v[206:207]
	v_cndmask_b32_e32 v2, v2, v4, vcc
	v_lshlrev_b32_e32 v91, 2, v2
	v_lshlrev_b32_e32 v2, 3, v228
	v_lshlrev_b32_e32 v1, 2, v1
	v_lshl_add_u64 v[70:71], s[74:75], 0, v[2:3]
	v_lshl_add_u64 v[78:79], v[68:69], 0, s[0:1]
	s_movk_i32 s14, 0x1000
	s_mov_b32 s4, 0x3a000000
	v_mov_b32_e32 v80, 0x358637bd
	s_mov_b32 s15, 0x800000
	v_mov_b32_e32 v92, 1
	s_mov_b32 s98, 0x8000
	s_mov_b32 s99, -1
	s_cmpk_lg_i32 s94, 0x100
	s_cbranch_scc1 .Lrms_setup_done
	s_cmpk_lt_i32 s2, 0x40
	s_cbranch_scc0 .Lrms_hi
	s_movk_i32 s98, 0x2000
	s_branch .Lrms_setup_done
.Lrms_hi:
	s_sub_i32 s99, s96, 0x200
.Lrms_setup_done:
	s_mov_b32 s10, s96
.LBB0_221:
	s_ashr_i32 s11, s10, 31
	s_lshl_b64 s[0:1], s[10:11], 13
	s_add_i32 s8, s10, s70
	v_lshl_add_u64 v[2:3], v[66:67], 0, s[0:1]
	s_ashr_i32 s9, s8, 31
	global_load_dwordx4 v[62:65], v[2:3], off
	global_load_dwordx4 v[54:57], v[2:3], off offset:1024
	global_load_dwordx4 v[42:45], v[2:3], off offset:2048
	s_lshl_b64 s[0:1], s[8:9], 13
	global_load_dwordx4 v[34:37], v[2:3], off offset:3072
	v_lshl_add_u64 v[4:5], v[66:67], 0, s[0:1]
	v_add_co_u32_e32 v2, vcc, 0x1000, v2
	global_load_dwordx4 v[58:61], v[4:5], off
	global_load_dwordx4 v[50:53], v[4:5], off offset:1024
	global_load_dwordx4 v[46:49], v[4:5], off offset:2048
	v_addc_co_u32_e32 v3, vcc, 0, v3, vcc
	global_load_dwordx4 v[26:29], v[2:3], off
	v_add_co_u32_e32 v6, vcc, s14, v4
	s_waitcnt vmcnt(7)
	v_mov_b32_e32 v84, v63
	v_addc_co_u32_e32 v7, vcc, 0, v5, vcc
	global_load_dwordx4 v[30:33], v[6:7], off
	global_load_dwordx4 v[38:41], v[4:5], off offset:3072
	global_load_dwordx4 v[22:25], v[2:3], off offset:1024
	global_load_dwordx4 v[18:21], v[6:7], off offset:1024
	global_load_dwordx4 v[14:17], v[2:3], off offset:2048
	s_nop 0
	global_load_dwordx4 v[2:5], v[2:3], off offset:3072
	s_nop 0
	global_load_dwordx4 v[10:13], v[6:7], off offset:2048
	s_nop 0
	global_load_dwordx4 v[6:9], v[6:7], off offset:3072
	s_waitcnt vmcnt(14)
	v_mov_b32_e32 v85, v55
	v_mov_b32_e32 v96, v65
	v_mov_b32_e32 v97, v57
	v_mov_b32_e32 v82, v62
	v_mov_b32_e32 v83, v54
	v_mov_b32_e32 v94, v64
	v_mov_b32_e32 v95, v56
	s_waitcnt vmcnt(13)
	v_pk_mul_f32 v[98:99], v[44:45], v[44:45]
	v_pk_mul_f32 v[100:101], v[42:43], v[42:43]
	v_pk_mul_f32 v[84:85], v[84:85], v[84:85]
	v_pk_mul_f32 v[96:97], v[96:97], v[96:97]
	v_pk_mov_b32 v[110:111], v[100:101], v[98:99] op_sel:[1,0]
	v_mov_b32_e32 v101, v99
	v_pk_fma_f32 v[82:83], v[82:83], v[82:83], v[84:85]
	v_pk_fma_f32 v[84:85], v[94:95], v[94:95], v[96:97]
	s_waitcnt vmcnt(12)
	v_mul_f32_e32 v86, v35, v35
	v_mul_f32_e32 v88, v37, v37
	s_waitcnt vmcnt(11)
	v_mov_b32_e32 v104, v59
	s_waitcnt vmcnt(10)
	v_mov_b32_e32 v105, v51
	v_mov_b32_e32 v108, v61
	v_mov_b32_e32 v109, v53
	s_waitcnt vmcnt(9)
	v_pk_mul_f32 v[98:99], v[48:49], v[48:49]
	v_pk_mul_f32 v[112:113], v[46:47], v[46:47]
	v_pk_add_f32 v[100:101], v[110:111], v[100:101]
	v_pk_add_f32 v[82:83], v[82:83], v[84:85]
	v_mov_b32_e32 v102, v58
	v_mov_b32_e32 v103, v50
	v_mov_b32_e32 v106, v60
	v_mov_b32_e32 v107, v52
	v_pk_fma_f32 v[114:115], v[34:35], v[34:35], v[86:87] op_sel_hi:[1,1,0]
	v_pk_fma_f32 v[116:117], v[36:37], v[36:37], v[88:89] op_sel_hi:[1,1,0]
	v_pk_mul_f32 v[94:95], v[104:105], v[104:105]
	v_pk_mul_f32 v[96:97], v[108:109], v[108:109]
	v_pk_mov_b32 v[104:105], v[112:113], v[98:99] op_sel:[1,0]
	v_mov_b32_e32 v113, v99
	s_waitcnt vmcnt(8)
	v_mul_f32_e32 v86, v26, v26
	v_mul_f32_e32 v88, v27, v27
	v_pk_add_f32 v[98:99], v[100:101], v[100:101] op_sel:[0,1] op_sel_hi:[1,0]
	v_pk_add_f32 v[82:83], v[82:83], v[82:83] op_sel:[0,1] op_sel_hi:[1,0]
	v_mul_f32_e32 v115, v28, v28
	v_mul_f32_e32 v117, v29, v29
	v_pk_fma_f32 v[84:85], v[102:103], v[102:103], v[94:95]
	v_pk_fma_f32 v[94:95], v[106:107], v[106:107], v[96:97]
	v_mov_b32_e32 v99, v88
	v_mov_b32_e32 v83, v86
	v_pk_add_f32 v[96:97], v[104:105], v[112:113]
	v_pk_add_f32 v[84:85], v[84:85], v[94:95]
	v_pk_add_f32 v[94:95], v[114:115], v[116:117]
	v_pk_add_f32 v[82:83], v[82:83], v[98:99]
	v_pk_add_f32 v[84:85], v[84:85], v[84:85] op_sel:[0,1] op_sel_hi:[1,0]
	v_pk_add_f32 v[82:83], v[82:83], v[94:95]
	v_pk_add_f32 v[94:95], v[96:97], v[96:97] op_sel:[0,1] op_sel_hi:[1,0]
	v_pk_add_f32 v[82:83], v[82:83], v[82:83] op_sel:[0,1] op_sel_hi:[1,0]
	s_waitcnt vmcnt(7)
; __device__ __forceinline__ unsigned pk2(float lo, float hi) { return f2bf(lo) | (f2bf(hi) << 16); }
; __device__ __forceinline__ void rms_row2_bf16(const float* x0, const float* x1, const float* gain, bf16_t* o0, bf16_t* o1, int lane) {
;     ...
;     for (int j = 0; j < 8; ++j) { sa += (va[j][0] * va[j][0] + va[j][1] * va[j][1]) + (va[j][2] * va[j][2] + va[j][3] * va[j][3]); sb += (vb[j][0] * vb[j][0] + vb[j][1] * vb[j][1]) + (vb[j][2] * vb[j][2] + vb[j][3] * vb[j][3]); }
;     const float ra = rsqrtf(wave_sum(sa) * (1.f / DM) + EPS), rb = rsqrtf(wave_sum(sb) * (1.f / DM) + EPS);
;     u32x2* pa = (u32x2*)o0 + lane; u32x2* pb = (u32x2*)o1 + lane;
; #pragma unroll
;     for (int j = 0; j < 8; ++j) { const f32x4 g = gr[64 * j]; u32x2 w; w.x = pk2(va[j][0] * ra * g[0], va[j][1] * ra * g[1]); w.y = pk2(va[j][2] * ra * g[2], va[j][3] * ra * g[3]); pa[64 * j] = w;
	v_mul_f32_e32 v93, v30, v30
	v_mul_f32_e32 v100, v31, v31
	v_mov_b32_e32 v85, v93
	v_mov_b32_e32 v95, v100
	s_waitcnt vmcnt(6)
	v_mul_f32_e32 v86, v39, v39
	v_pk_add_f32 v[84:85], v[84:85], v[94:95]
	v_pk_fma_f32 v[94:95], v[38:39], v[38:39], v[86:87] op_sel_hi:[1,1,0]
	v_mul_f32_e32 v86, v41, v41
	v_mul_f32_e32 v101, v32, v32
	v_mul_f32_e32 v102, v33, v33
	v_pk_fma_f32 v[96:97], v[40:41], v[40:41], v[86:87] op_sel_hi:[1,1,0]
	v_mov_b32_e32 v95, v101
	v_mov_b32_e32 v97, v102
	v_pk_add_f32 v[94:95], v[94:95], v[96:97]
	s_waitcnt vmcnt(5)
	v_pk_mul_f32 v[96:97], v[22:23], v[22:23]
	v_pk_add_f32 v[84:85], v[84:85], v[94:95]
	v_pk_mul_f32 v[94:95], v[24:25], v[24:25]
	s_waitcnt vmcnt(2)
	v_mul_f32_e32 v86, v2, v2
	v_pk_mov_b32 v[98:99], v[96:97], v[94:95] op_sel:[1,0]
	v_mov_b32_e32 v97, v95
	v_pk_add_f32 v[94:95], v[98:99], v[96:97]
	v_mul_f32_e32 v88, v3, v3
	v_pk_add_f32 v[94:95], v[94:95], v[94:95] op_sel:[0,1] op_sel_hi:[1,0]
	v_pk_mul_f32 v[96:97], v[20:21], v[20:21]
	v_pk_mul_f32 v[98:99], v[18:19], v[18:19]
	v_mov_b32_e32 v83, v86
	v_mov_b32_e32 v95, v88
	v_mul_f32_e32 v86, v15, v15
	v_pk_mov_b32 v[100:101], v[98:99], v[96:97] op_sel:[1,0]
	v_mov_b32_e32 v99, v97
	v_pk_add_f32 v[82:83], v[82:83], v[94:95]
	v_pk_fma_f32 v[94:95], v[14:15], v[14:15], v[86:87] op_sel_hi:[1,1,0]
	v_mul_f32_e32 v86, v17, v17
	v_pk_add_f32 v[98:99], v[100:101], v[98:99]
	v_mul_f32_e32 v93, v4, v4
	v_mul_f32_e32 v100, v5, v5
	v_pk_fma_f32 v[96:97], v[16:17], v[16:17], v[86:87] op_sel_hi:[1,1,0]
	v_mov_b32_e32 v95, v93
	v_mov_b32_e32 v97, v100
	v_pk_add_f32 v[94:95], v[94:95], v[96:97]
	s_waitcnt vmcnt(0)
	v_mul_f32_e32 v86, v6, v6
	v_pk_add_f32 v[82:83], v[82:83], v[94:95]
	global_load_dwordx4 v[94:97], v[68:69], off
	v_mul_f32_e32 v88, v7, v7
	v_pk_add_f32 v[84:85], v[84:85], v[84:85] op_sel:[0,1] op_sel_hi:[1,0]
	v_pk_add_f32 v[98:99], v[98:99], v[98:99] op_sel:[0,1] op_sel_hi:[1,0]
	v_mov_b32_e32 v85, v86
	v_mov_b32_e32 v99, v88
	v_mul_f32_e32 v86, v11, v11
	v_pk_add_f32 v[84:85], v[84:85], v[98:99]
	v_pk_fma_f32 v[98:99], v[10:11], v[10:11], v[86:87] op_sel_hi:[1,1,0]
	v_mul_f32_e32 v86, v13, v13
	v_mul_f32_e32 v93, v8, v8
	v_mul_f32_e32 v102, v9, v9
	v_pk_fma_f32 v[100:101], v[12:13], v[12:13], v[86:87] op_sel_hi:[1,1,0]
	v_mov_b32_e32 v99, v93
	v_mov_b32_e32 v101, v102
	v_pk_add_f32 v[98:99], v[98:99], v[100:101]
	s_waitcnt vmcnt(0)
	v_mov_b32_e32 v101, v96
	v_pk_add_f32 v[84:85], v[84:85], v[98:99]
	v_mov_b32_e32 v99, v82
	v_mov_b32_e32 v98, v84
	v_mov_b32_e32 v82, v85
	v_pk_add_f32 v[82:83], v[98:99], v[82:83]
	ds_bpermute_b32 v85, v1, v83
	ds_bpermute_b32 v84, v1, v82
	v_mov_b32_e32 v99, v64
	v_mov_b32_e32 v64, v63
	v_mov_b32_e32 v98, v62
	v_mov_b32_e32 v96, v95
	s_waitcnt lgkmcnt(0)
	v_pk_add_f32 v[82:83], v[82:83], v[84:85]
	ds_bpermute_b32 v85, v81, v83
	ds_bpermute_b32 v84, v81, v82
	v_mov_b32_e32 v100, v94
	s_waitcnt lgkmcnt(0)
	v_pk_add_f32 v[82:83], v[82:83], v[84:85]
	ds_bpermute_b32 v85, v87, v83
	ds_bpermute_b32 v84, v87, v82
	s_waitcnt lgkmcnt(0)
	v_pk_add_f32 v[82:83], v[82:83], v[84:85]
	ds_bpermute_b32 v85, v89, v83
	ds_bpermute_b32 v84, v89, v82
	s_waitcnt lgkmcnt(0)
	v_pk_add_f32 v[82:83], v[82:83], v[84:85]
	ds_bpermute_b32 v85, v90, v83
	ds_bpermute_b32 v84, v90, v82
	s_waitcnt lgkmcnt(0)
	v_pk_add_f32 v[82:83], v[82:83], v[84:85]
	ds_bpermute_b32 v85, v91, v83
	ds_bpermute_b32 v84, v91, v82
	s_waitcnt lgkmcnt(0)
	v_pk_add_f32 v[82:83], v[82:83], v[84:85]
	s_nop 0
	v_pk_fma_f32 v[82:83], v[82:83], s[4:5], v[80:81] op_sel_hi:[1,0,0]
	s_nop 0
	v_mul_f32_e32 v84, 0x4b800000, v83
	v_cmp_gt_f32_e32 vcc, s15, v83
	v_cmp_gt_f32_e64 s[0:1], s15, v82
	s_nop 0
	v_cndmask_b32_e32 v83, v83, v84, vcc
	v_rsq_f32_e32 v83, v83
	v_mul_f32_e32 v84, 0x4b800000, v82
	v_cndmask_b32_e64 v82, v82, v84, s[0:1]
	v_rsq_f32_e32 v82, v82
	v_mul_f32_e32 v84, 0x45800000, v83
	v_cndmask_b32_e32 v86, v83, v84, vcc
	v_pk_mul_f32 v[62:63], v[64:65], v[86:87] op_sel_hi:[1,0]
	v_pk_mul_f32 v[98:99], v[98:99], v[86:87] op_sel_hi:[1,0]
	v_pk_mul_f32 v[62:63], v[96:97], v[62:63]
	v_pk_mul_f32 v[98:99], v[100:101], v[98:99]
	v_and_b32_sdwa v93, v63, v92 dst_sel:DWORD dst_unused:UNUSED_PAD src0_sel:WORD_1 src1_sel:DWORD
	v_and_b32_sdwa v94, v62, v92 dst_sel:DWORD dst_unused:UNUSED_PAD src0_sel:WORD_1 src1_sel:DWORD
	v_mul_f32_e32 v83, 0x45800000, v82
	v_and_b32_sdwa v64, v99, v92 dst_sel:DWORD dst_unused:UNUSED_PAD src0_sel:WORD_1 src1_sel:DWORD
	v_and_b32_sdwa v65, v98, v92 dst_sel:DWORD dst_unused:UNUSED_PAD src0_sel:WORD_1 src1_sel:DWORD
	v_add3_u32 v63, v63, v93, s5
	v_add3_u32 v62, v62, v94, s5
	v_cndmask_b32_e64 v88, v82, v83, s[0:1]
	s_lshl_b64 s[0:1], s[10:11], 12
	v_add3_u32 v65, v98, v65, s5
	v_add3_u32 v64, v99, v64, s5
	v_and_b32_e32 v63, 0xffff0000, v63
	v_and_b32_e32 v62, 0xffff0000, v62
	v_lshl_add_u64 v[82:83], v[70:71], 0, s[0:1]
	v_or_b32_sdwa v63, v63, v64 dst_sel:DWORD dst_unused:UNUSED_PAD src0_sel:DWORD src1_sel:WORD_1
	v_or_b32_sdwa v62, v62, v65 dst_sel:DWORD dst_unused:UNUSED_PAD src0_sel:DWORD src1_sel:WORD_1
	global_store_dwordx2 v[82:83], v[62:63], off
	v_mov_b32_e32 v62, v58
	v_mov_b32_e32 v63, v60
	v_pk_mul_f32 v[62:63], v[62:63], v[88:89] op_sel_hi:[1,0]
	v_mov_b32_e32 v60, v59
	v_pk_mul_f32 v[62:63], v[100:101], v[62:63]
	v_pk_mul_f32 v[58:59], v[60:61], v[88:89] op_sel_hi:[1,0]
	v_and_b32_sdwa v60, v63, v92 dst_sel:DWORD dst_unused:UNUSED_PAD src0_sel:WORD_1 src1_sel:DWORD
	v_pk_mul_f32 v[58:59], v[96:97], v[58:59]
	v_and_b32_sdwa v61, v62, v92 dst_sel:DWORD dst_unused:UNUSED_PAD src0_sel:WORD_1 src1_sel:DWORD
	v_add3_u32 v61, v62, v61, s5
	v_add3_u32 v60, v63, v60, s5
	v_and_b32_sdwa v62, v59, v92 dst_sel:DWORD dst_unused:UNUSED_PAD src0_sel:WORD_1 src1_sel:DWORD
	v_and_b32_sdwa v63, v58, v92 dst_sel:DWORD dst_unused:UNUSED_PAD src0_sel:WORD_1 src1_sel:DWORD
	v_add3_u32 v59, v59, v62, s5
	v_add3_u32 v58, v58, v63, s5
	s_lshl_b64 s[0:1], s[8:9], 12
	v_and_b32_e32 v59, 0xffff0000, v59
	v_and_b32_e32 v58, 0xffff0000, v58
	v_lshl_add_u64 v[84:85], v[70:71], 0, s[0:1]
	v_or_b32_sdwa v59, v59, v60 dst_sel:DWORD dst_unused:UNUSED_PAD src0_sel:DWORD src1_sel:WORD_1
	v_or_b32_sdwa v58, v58, v61 dst_sel:DWORD dst_unused:UNUSED_PAD src0_sel:DWORD src1_sel:WORD_1
	global_store_dwordx2 v[84:85], v[58:59], off
	global_load_dwordx4 v[58:61], v[68:69], off offset:1024
	v_mov_b32_e32 v63, v56
	v_mov_b32_e32 v56, v55
	v_mov_b32_e32 v62, v54
	v_pk_mul_f32 v[54:55], v[56:57], v[86:87] op_sel_hi:[1,0]
	v_pk_mul_f32 v[62:63], v[62:63], v[86:87] op_sel_hi:[1,0]
	s_add_i32 s10, s8, s70
	s_cmp_ge_i32 s10, s98
	s_waitcnt vmcnt(0)
; __device__ __forceinline__ unsigned pk2(float lo, float hi) { return f2bf(lo) | (f2bf(hi) << 16); }
; __device__ __forceinline__ void rms_row2_bf16(const float* x0, const float* x1, const float* gain, bf16_t* o0, bf16_t* o1, int lane) {
;     ...
;     for (int j = 0; j < 8; ++j) { const f32x4 g = gr[64 * j]; u32x2 w; w.x = pk2(va[j][0] * ra * g[0], va[j][1] * ra * g[1]); w.y = pk2(va[j][2] * ra * g[2], va[j][3] * ra * g[3]); pa[64 * j] = w;
;         u32x2 w2; w2.x = pk2(vb[j][0] * rb * g[0], vb[j][1] * rb * g[1]); w2.y = pk2(vb[j][2] * rb * g[2], vb[j][3] * rb * g[3]); pb[64 * j] = w2; }
	v_mov_b32_e32 v65, v60
	v_mov_b32_e32 v60, v59
	v_mov_b32_e32 v64, v58
	v_pk_mul_f32 v[54:55], v[54:55], v[60:61]
	v_pk_mul_f32 v[62:63], v[62:63], v[64:65]
	v_and_b32_sdwa v58, v55, v92 dst_sel:DWORD dst_unused:UNUSED_PAD src0_sel:WORD_1 src1_sel:DWORD
	v_and_b32_sdwa v59, v54, v92 dst_sel:DWORD dst_unused:UNUSED_PAD src0_sel:WORD_1 src1_sel:DWORD
	v_and_b32_sdwa v56, v63, v92 dst_sel:DWORD dst_unused:UNUSED_PAD src0_sel:WORD_1 src1_sel:DWORD
	v_and_b32_sdwa v57, v62, v92 dst_sel:DWORD dst_unused:UNUSED_PAD src0_sel:WORD_1 src1_sel:DWORD
	v_add3_u32 v55, v55, v58, s5
	v_add3_u32 v54, v54, v59, s5
	v_add3_u32 v57, v62, v57, s5
	v_add3_u32 v56, v63, v56, s5
	v_and_b32_e32 v55, 0xffff0000, v55
	v_and_b32_e32 v54, 0xffff0000, v54
	v_or_b32_sdwa v55, v55, v56 dst_sel:DWORD dst_unused:UNUSED_PAD src0_sel:DWORD src1_sel:WORD_1
	v_or_b32_sdwa v54, v54, v57 dst_sel:DWORD dst_unused:UNUSED_PAD src0_sel:DWORD src1_sel:WORD_1
	global_store_dwordx2 v[82:83], v[54:55], off offset:512
	v_mov_b32_e32 v54, v50
	v_mov_b32_e32 v55, v52
	v_pk_mul_f32 v[54:55], v[54:55], v[88:89] op_sel_hi:[1,0]
	v_mov_b32_e32 v52, v51
	v_pk_mul_f32 v[54:55], v[64:65], v[54:55]
	v_pk_mul_f32 v[50:51], v[52:53], v[88:89] op_sel_hi:[1,0]
	v_and_b32_sdwa v52, v55, v92 dst_sel:DWORD dst_unused:UNUSED_PAD src0_sel:WORD_1 src1_sel:DWORD
	v_pk_mul_f32 v[50:51], v[60:61], v[50:51]
	v_and_b32_sdwa v53, v54, v92 dst_sel:DWORD dst_unused:UNUSED_PAD src0_sel:WORD_1 src1_sel:DWORD
	v_add3_u32 v53, v54, v53, s5
	v_add3_u32 v52, v55, v52, s5
	v_and_b32_sdwa v54, v51, v92 dst_sel:DWORD dst_unused:UNUSED_PAD src0_sel:WORD_1 src1_sel:DWORD
	v_and_b32_sdwa v55, v50, v92 dst_sel:DWORD dst_unused:UNUSED_PAD src0_sel:WORD_1 src1_sel:DWORD
	v_add3_u32 v51, v51, v54, s5
	v_add3_u32 v50, v50, v55, s5
	v_and_b32_e32 v51, 0xffff0000, v51
	v_and_b32_e32 v50, 0xffff0000, v50
	v_or_b32_sdwa v51, v51, v52 dst_sel:DWORD dst_unused:UNUSED_PAD src0_sel:DWORD src1_sel:WORD_1
	v_or_b32_sdwa v50, v50, v53 dst_sel:DWORD dst_unused:UNUSED_PAD src0_sel:DWORD src1_sel:WORD_1
	global_store_dwordx2 v[84:85], v[50:51], off offset:512
	global_load_dwordx4 v[50:53], v[68:69], off offset:2048
	v_mov_b32_e32 v54, v42
	v_mov_b32_e32 v55, v44
	v_mov_b32_e32 v44, v43
	v_mov_b32_e32 v42, v46
	v_mov_b32_e32 v43, v48
	v_mov_b32_e32 v48, v47
	v_pk_mul_f32 v[46:47], v[54:55], v[86:87] op_sel_hi:[1,0]
	v_pk_mul_f32 v[44:45], v[44:45], v[86:87] op_sel_hi:[1,0]
	v_pk_mul_f32 v[42:43], v[42:43], v[88:89] op_sel_hi:[1,0]
	v_pk_mul_f32 v[48:49], v[48:49], v[88:89] op_sel_hi:[1,0]
	s_waitcnt vmcnt(0)
	v_mov_b32_e32 v55, v52
	v_mov_b32_e32 v52, v51
	v_mov_b32_e32 v54, v50
	v_pk_mul_f32 v[44:45], v[44:45], v[52:53]
	v_pk_mul_f32 v[46:47], v[46:47], v[54:55]
	v_pk_mul_f32 v[42:43], v[54:55], v[42:43]
	v_pk_mul_f32 v[48:49], v[52:53], v[48:49]
	v_and_b32_sdwa v52, v45, v92 dst_sel:DWORD dst_unused:UNUSED_PAD src0_sel:WORD_1 src1_sel:DWORD
	v_and_b32_sdwa v53, v44, v92 dst_sel:DWORD dst_unused:UNUSED_PAD src0_sel:WORD_1 src1_sel:DWORD
	v_and_b32_sdwa v50, v47, v92 dst_sel:DWORD dst_unused:UNUSED_PAD src0_sel:WORD_1 src1_sel:DWORD
	v_and_b32_sdwa v51, v46, v92 dst_sel:DWORD dst_unused:UNUSED_PAD src0_sel:WORD_1 src1_sel:DWORD
	v_and_b32_sdwa v54, v43, v92 dst_sel:DWORD dst_unused:UNUSED_PAD src0_sel:WORD_1 src1_sel:DWORD
	v_and_b32_sdwa v55, v42, v92 dst_sel:DWORD dst_unused:UNUSED_PAD src0_sel:WORD_1 src1_sel:DWORD
	v_and_b32_sdwa v56, v49, v92 dst_sel:DWORD dst_unused:UNUSED_PAD src0_sel:WORD_1 src1_sel:DWORD
	v_and_b32_sdwa v57, v48, v92 dst_sel:DWORD dst_unused:UNUSED_PAD src0_sel:WORD_1 src1_sel:DWORD
	v_add3_u32 v45, v45, v52, s5
	v_add3_u32 v44, v44, v53, s5
	v_add3_u32 v46, v46, v51, s5
	v_add3_u32 v47, v47, v50, s5
	v_add3_u32 v50, v42, v55, s5
	v_add3_u32 v51, v43, v54, s5
	v_add3_u32 v42, v49, v56, s5
	v_add3_u32 v43, v48, v57, s5
	v_and_b32_e32 v45, 0xffff0000, v45
	v_and_b32_e32 v44, 0xffff0000, v44
	v_and_b32_e32 v48, 0xffff0000, v42
	v_and_b32_e32 v49, 0xffff0000, v43
	v_or_b32_sdwa v43, v45, v47 dst_sel:DWORD dst_unused:UNUSED_PAD src0_sel:DWORD src1_sel:WORD_1
	v_or_b32_sdwa v42, v44, v46 dst_sel:DWORD dst_unused:UNUSED_PAD src0_sel:DWORD src1_sel:WORD_1
	v_or_b32_sdwa v45, v48, v51 dst_sel:DWORD dst_unused:UNUSED_PAD src0_sel:DWORD src1_sel:WORD_1
	v_or_b32_sdwa v44, v49, v50 dst_sel:DWORD dst_unused:UNUSED_PAD src0_sel:DWORD src1_sel:WORD_1
	global_store_dwordx2 v[82:83], v[42:43], off offset:1024
	global_store_dwordx2 v[84:85], v[44:45], off offset:1024
	global_load_dwordx4 v[42:45], v[68:69], off offset:3072
	v_mov_b32_e32 v46, v34
	v_mov_b32_e32 v47, v36
	v_mov_b32_e32 v36, v35
	v_mov_b32_e32 v34, v38
	v_mov_b32_e32 v35, v40
	v_mov_b32_e32 v40, v39
	v_pk_mul_f32 v[38:39], v[46:47], v[86:87] op_sel_hi:[1,0]
	v_pk_mul_f32 v[36:37], v[36:37], v[86:87] op_sel_hi:[1,0]
	v_pk_mul_f32 v[34:35], v[34:35], v[88:89] op_sel_hi:[1,0]
	v_pk_mul_f32 v[40:41], v[40:41], v[88:89] op_sel_hi:[1,0]
	s_waitcnt vmcnt(0)
; __device__ __forceinline__ unsigned pk2(float lo, float hi) { return f2bf(lo) | (f2bf(hi) << 16); }
; __device__ __forceinline__ void rms_row2_bf16(const float* x0, const float* x1, const float* gain, bf16_t* o0, bf16_t* o1, int lane) {
;     ...
;     for (int j = 0; j < 8; ++j) { const f32x4 g = gr[64 * j]; u32x2 w; w.x = pk2(va[j][0] * ra * g[0], va[j][1] * ra * g[1]); w.y = pk2(va[j][2] * ra * g[2], va[j][3] * ra * g[3]); pa[64 * j] = w;
;         u32x2 w2; w2.x = pk2(vb[j][0] * rb * g[0], vb[j][1] * rb * g[1]); w2.y = pk2(vb[j][2] * rb * g[2], vb[j][3] * rb * g[3]); pb[64 * j] = w2; }
	v_mov_b32_e32 v47, v44
	v_mov_b32_e32 v44, v43
	v_mov_b32_e32 v46, v42
	v_pk_mul_f32 v[36:37], v[36:37], v[44:45]
	v_pk_mul_f32 v[38:39], v[38:39], v[46:47]
	v_pk_mul_f32 v[34:35], v[34:35], v[46:47]
	v_pk_mul_f32 v[40:41], v[40:41], v[44:45]
	v_and_b32_sdwa v44, v37, v92 dst_sel:DWORD dst_unused:UNUSED_PAD src0_sel:WORD_1 src1_sel:DWORD
	v_and_b32_sdwa v45, v36, v92 dst_sel:DWORD dst_unused:UNUSED_PAD src0_sel:WORD_1 src1_sel:DWORD
	v_and_b32_sdwa v42, v39, v92 dst_sel:DWORD dst_unused:UNUSED_PAD src0_sel:WORD_1 src1_sel:DWORD
	v_and_b32_sdwa v43, v38, v92 dst_sel:DWORD dst_unused:UNUSED_PAD src0_sel:WORD_1 src1_sel:DWORD
	v_and_b32_sdwa v46, v35, v92 dst_sel:DWORD dst_unused:UNUSED_PAD src0_sel:WORD_1 src1_sel:DWORD
	v_and_b32_sdwa v47, v34, v92 dst_sel:DWORD dst_unused:UNUSED_PAD src0_sel:WORD_1 src1_sel:DWORD
	v_and_b32_sdwa v48, v41, v92 dst_sel:DWORD dst_unused:UNUSED_PAD src0_sel:WORD_1 src1_sel:DWORD
	v_and_b32_sdwa v49, v40, v92 dst_sel:DWORD dst_unused:UNUSED_PAD src0_sel:WORD_1 src1_sel:DWORD
	v_add3_u32 v37, v37, v44, s5
	v_add3_u32 v36, v36, v45, s5
	v_add3_u32 v38, v38, v43, s5
	v_add3_u32 v39, v39, v42, s5
	v_add3_u32 v42, v34, v47, s5
	v_add3_u32 v43, v35, v46, s5
	v_add3_u32 v34, v41, v48, s5
	v_add3_u32 v35, v40, v49, s5
	v_and_b32_e32 v37, 0xffff0000, v37
	v_and_b32_e32 v36, 0xffff0000, v36
	v_and_b32_e32 v40, 0xffff0000, v34
	v_and_b32_e32 v41, 0xffff0000, v35
	v_or_b32_sdwa v35, v37, v39 dst_sel:DWORD dst_unused:UNUSED_PAD src0_sel:DWORD src1_sel:WORD_1
	v_or_b32_sdwa v34, v36, v38 dst_sel:DWORD dst_unused:UNUSED_PAD src0_sel:DWORD src1_sel:WORD_1
	v_or_b32_sdwa v37, v40, v43 dst_sel:DWORD dst_unused:UNUSED_PAD src0_sel:DWORD src1_sel:WORD_1
	v_or_b32_sdwa v36, v41, v42 dst_sel:DWORD dst_unused:UNUSED_PAD src0_sel:DWORD src1_sel:WORD_1
	global_store_dwordx2 v[82:83], v[34:35], off offset:1536
	global_store_dwordx2 v[84:85], v[36:37], off offset:1536
	global_load_dwordx4 v[34:37], v[72:73], off
	v_mov_b32_e32 v38, v26
	v_mov_b32_e32 v39, v28
	v_mov_b32_e32 v28, v27
	v_mov_b32_e32 v26, v30
	v_mov_b32_e32 v27, v32
	v_mov_b32_e32 v32, v31
	v_pk_mul_f32 v[30:31], v[38:39], v[86:87] op_sel_hi:[1,0]
	v_pk_mul_f32 v[28:29], v[28:29], v[86:87] op_sel_hi:[1,0]
	v_pk_mul_f32 v[26:27], v[26:27], v[88:89] op_sel_hi:[1,0]
	v_pk_mul_f32 v[32:33], v[32:33], v[88:89] op_sel_hi:[1,0]
	s_waitcnt vmcnt(0)
	v_mov_b32_e32 v39, v36
	v_mov_b32_e32 v36, v35
	v_mov_b32_e32 v38, v34
	v_pk_mul_f32 v[28:29], v[28:29], v[36:37]
	v_pk_mul_f32 v[30:31], v[30:31], v[38:39]
	v_pk_mul_f32 v[26:27], v[26:27], v[38:39]
	v_pk_mul_f32 v[32:33], v[32:33], v[36:37]
	v_and_b32_sdwa v36, v29, v92 dst_sel:DWORD dst_unused:UNUSED_PAD src0_sel:WORD_1 src1_sel:DWORD
	v_and_b32_sdwa v37, v28, v92 dst_sel:DWORD dst_unused:UNUSED_PAD src0_sel:WORD_1 src1_sel:DWORD
	v_and_b32_sdwa v34, v31, v92 dst_sel:DWORD dst_unused:UNUSED_PAD src0_sel:WORD_1 src1_sel:DWORD
	v_and_b32_sdwa v35, v30, v92 dst_sel:DWORD dst_unused:UNUSED_PAD src0_sel:WORD_1 src1_sel:DWORD
	v_and_b32_sdwa v38, v27, v92 dst_sel:DWORD dst_unused:UNUSED_PAD src0_sel:WORD_1 src1_sel:DWORD
	v_and_b32_sdwa v39, v26, v92 dst_sel:DWORD dst_unused:UNUSED_PAD src0_sel:WORD_1 src1_sel:DWORD
	v_and_b32_sdwa v40, v33, v92 dst_sel:DWORD dst_unused:UNUSED_PAD src0_sel:WORD_1 src1_sel:DWORD
	v_and_b32_sdwa v41, v32, v92 dst_sel:DWORD dst_unused:UNUSED_PAD src0_sel:WORD_1 src1_sel:DWORD
	v_add3_u32 v29, v29, v36, s5
	v_add3_u32 v28, v28, v37, s5
	v_add3_u32 v30, v30, v35, s5
	v_add3_u32 v31, v31, v34, s5
	v_add3_u32 v34, v26, v39, s5
	v_add3_u32 v35, v27, v38, s5
	v_add3_u32 v26, v33, v40, s5
	v_add3_u32 v27, v32, v41, s5
	v_and_b32_e32 v29, 0xffff0000, v29
	v_and_b32_e32 v28, 0xffff0000, v28
	v_and_b32_e32 v32, 0xffff0000, v26
	v_and_b32_e32 v33, 0xffff0000, v27
	v_or_b32_sdwa v27, v29, v31 dst_sel:DWORD dst_unused:UNUSED_PAD src0_sel:DWORD src1_sel:WORD_1
	v_or_b32_sdwa v26, v28, v30 dst_sel:DWORD dst_unused:UNUSED_PAD src0_sel:DWORD src1_sel:WORD_1
	v_or_b32_sdwa v29, v32, v35 dst_sel:DWORD dst_unused:UNUSED_PAD src0_sel:DWORD src1_sel:WORD_1
	v_or_b32_sdwa v28, v33, v34 dst_sel:DWORD dst_unused:UNUSED_PAD src0_sel:DWORD src1_sel:WORD_1
	global_store_dwordx2 v[82:83], v[26:27], off offset:2048
	global_store_dwordx2 v[84:85], v[28:29], off offset:2048
	global_load_dwordx4 v[26:29], v[74:75], off
	v_mov_b32_e32 v30, v22
	v_mov_b32_e32 v31, v24
	v_mov_b32_e32 v24, v23
	v_mov_b32_e32 v22, v18
	v_mov_b32_e32 v23, v20
	v_mov_b32_e32 v20, v19
	v_pk_mul_f32 v[18:19], v[30:31], v[86:87] op_sel_hi:[1,0]
	v_pk_mul_f32 v[24:25], v[24:25], v[86:87] op_sel_hi:[1,0]
	v_pk_mul_f32 v[20:21], v[20:21], v[88:89] op_sel_hi:[1,0]
	v_pk_mul_f32 v[22:23], v[22:23], v[88:89] op_sel_hi:[1,0]
	s_waitcnt vmcnt(0)
; __device__ __forceinline__ unsigned pk2(float lo, float hi) { return f2bf(lo) | (f2bf(hi) << 16); }
; __device__ __forceinline__ void rms_row2_bf16(const float* x0, const float* x1, const float* gain, bf16_t* o0, bf16_t* o1, int lane) {
;     ...
;     for (int j = 0; j < 8; ++j) { const f32x4 g = gr[64 * j]; u32x2 w; w.x = pk2(va[j][0] * ra * g[0], va[j][1] * ra * g[1]); w.y = pk2(va[j][2] * ra * g[2], va[j][3] * ra * g[3]); pa[64 * j] = w;
;         u32x2 w2; w2.x = pk2(vb[j][0] * rb * g[0], vb[j][1] * rb * g[1]); w2.y = pk2(vb[j][2] * rb * g[2], vb[j][3] * rb * g[3]); pb[64 * j] = w2; }
; __global__ void __launch_bounds__(512, 2) fwd_mega(Args a) {
;     ...
;         for (int m = gw; m < MT; m += 2 * NGW) rms_row2_bf16(a.in[I_X] + (size_t)m * DM, a.in[I_X] + (size_t)(m + NGW) * DM, a.in[I_F1N], U + (size_t)m * DM, U + (size_t)(m + NGW) * DM, lane);
	v_mov_b32_e32 v31, v28
	v_mov_b32_e32 v28, v27
	v_mov_b32_e32 v30, v26
	v_pk_mul_f32 v[24:25], v[24:25], v[28:29]
	v_pk_mul_f32 v[18:19], v[18:19], v[30:31]
	v_pk_mul_f32 v[20:21], v[20:21], v[28:29]
	v_and_b32_sdwa v28, v25, v92 dst_sel:DWORD dst_unused:UNUSED_PAD src0_sel:WORD_1 src1_sel:DWORD
	v_and_b32_sdwa v29, v24, v92 dst_sel:DWORD dst_unused:UNUSED_PAD src0_sel:WORD_1 src1_sel:DWORD
	v_pk_mul_f32 v[22:23], v[22:23], v[30:31]
	v_and_b32_sdwa v26, v19, v92 dst_sel:DWORD dst_unused:UNUSED_PAD src0_sel:WORD_1 src1_sel:DWORD
	v_and_b32_sdwa v27, v18, v92 dst_sel:DWORD dst_unused:UNUSED_PAD src0_sel:WORD_1 src1_sel:DWORD
	v_and_b32_sdwa v32, v21, v92 dst_sel:DWORD dst_unused:UNUSED_PAD src0_sel:WORD_1 src1_sel:DWORD
	v_and_b32_sdwa v33, v20, v92 dst_sel:DWORD dst_unused:UNUSED_PAD src0_sel:WORD_1 src1_sel:DWORD
	v_add3_u32 v25, v25, v28, s5
	v_add3_u32 v24, v24, v29, s5
	v_and_b32_sdwa v30, v23, v92 dst_sel:DWORD dst_unused:UNUSED_PAD src0_sel:WORD_1 src1_sel:DWORD
	v_and_b32_sdwa v31, v22, v92 dst_sel:DWORD dst_unused:UNUSED_PAD src0_sel:WORD_1 src1_sel:DWORD
	v_add3_u32 v18, v18, v27, s5
	v_add3_u32 v19, v19, v26, s5
	v_add3_u32 v21, v21, v32, s5
	v_add3_u32 v20, v20, v33, s5
	v_and_b32_e32 v25, 0xffff0000, v25
	v_and_b32_e32 v24, 0xffff0000, v24
	v_add3_u32 v22, v22, v31, s5
	v_add3_u32 v23, v23, v30, s5
	v_and_b32_e32 v21, 0xffff0000, v21
	v_and_b32_e32 v20, 0xffff0000, v20
	v_or_b32_sdwa v19, v25, v19 dst_sel:DWORD dst_unused:UNUSED_PAD src0_sel:DWORD src1_sel:WORD_1
	v_or_b32_sdwa v18, v24, v18 dst_sel:DWORD dst_unused:UNUSED_PAD src0_sel:DWORD src1_sel:WORD_1
	v_or_b32_sdwa v21, v21, v23 dst_sel:DWORD dst_unused:UNUSED_PAD src0_sel:DWORD src1_sel:WORD_1
	v_or_b32_sdwa v20, v20, v22 dst_sel:DWORD dst_unused:UNUSED_PAD src0_sel:DWORD src1_sel:WORD_1
	global_store_dwordx2 v[82:83], v[18:19], off offset:2560
	global_store_dwordx2 v[84:85], v[20:21], off offset:2560
	global_load_dwordx4 v[18:21], v[76:77], off
	v_mov_b32_e32 v22, v14
	v_mov_b32_e32 v23, v16
	v_mov_b32_e32 v16, v15
	v_mov_b32_e32 v14, v10
	v_mov_b32_e32 v15, v12
	v_mov_b32_e32 v12, v11
	v_pk_mul_f32 v[10:11], v[22:23], v[86:87] op_sel_hi:[1,0]
	v_pk_mul_f32 v[16:17], v[16:17], v[86:87] op_sel_hi:[1,0]
	v_pk_mul_f32 v[12:13], v[12:13], v[88:89] op_sel_hi:[1,0]
	v_pk_mul_f32 v[14:15], v[14:15], v[88:89] op_sel_hi:[1,0]
	s_waitcnt vmcnt(0)
	v_mov_b32_e32 v23, v20
	v_mov_b32_e32 v20, v19
	v_mov_b32_e32 v22, v18
	v_pk_mul_f32 v[16:17], v[16:17], v[20:21]
	v_pk_mul_f32 v[10:11], v[10:11], v[22:23]
	v_pk_mul_f32 v[12:13], v[12:13], v[20:21]
	v_and_b32_sdwa v20, v17, v92 dst_sel:DWORD dst_unused:UNUSED_PAD src0_sel:WORD_1 src1_sel:DWORD
	v_and_b32_sdwa v21, v16, v92 dst_sel:DWORD dst_unused:UNUSED_PAD src0_sel:WORD_1 src1_sel:DWORD
	v_pk_mul_f32 v[14:15], v[14:15], v[22:23]
	v_and_b32_sdwa v18, v11, v92 dst_sel:DWORD dst_unused:UNUSED_PAD src0_sel:WORD_1 src1_sel:DWORD
	v_and_b32_sdwa v19, v10, v92 dst_sel:DWORD dst_unused:UNUSED_PAD src0_sel:WORD_1 src1_sel:DWORD
	v_and_b32_sdwa v24, v13, v92 dst_sel:DWORD dst_unused:UNUSED_PAD src0_sel:WORD_1 src1_sel:DWORD
	v_and_b32_sdwa v25, v12, v92 dst_sel:DWORD dst_unused:UNUSED_PAD src0_sel:WORD_1 src1_sel:DWORD
	v_add3_u32 v17, v17, v20, s5
	v_add3_u32 v16, v16, v21, s5
	v_and_b32_sdwa v22, v15, v92 dst_sel:DWORD dst_unused:UNUSED_PAD src0_sel:WORD_1 src1_sel:DWORD
	v_and_b32_sdwa v23, v14, v92 dst_sel:DWORD dst_unused:UNUSED_PAD src0_sel:WORD_1 src1_sel:DWORD
	v_add3_u32 v10, v10, v19, s5
	v_add3_u32 v11, v11, v18, s5
	v_add3_u32 v13, v13, v24, s5
	v_add3_u32 v12, v12, v25, s5
	v_and_b32_e32 v17, 0xffff0000, v17
	v_and_b32_e32 v16, 0xffff0000, v16
	v_add3_u32 v14, v14, v23, s5
	v_add3_u32 v15, v15, v22, s5
	v_and_b32_e32 v13, 0xffff0000, v13
	v_and_b32_e32 v12, 0xffff0000, v12
	v_or_b32_sdwa v11, v17, v11 dst_sel:DWORD dst_unused:UNUSED_PAD src0_sel:DWORD src1_sel:WORD_1
	v_or_b32_sdwa v10, v16, v10 dst_sel:DWORD dst_unused:UNUSED_PAD src0_sel:DWORD src1_sel:WORD_1
	v_or_b32_sdwa v13, v13, v15 dst_sel:DWORD dst_unused:UNUSED_PAD src0_sel:DWORD src1_sel:WORD_1
	v_or_b32_sdwa v12, v12, v14 dst_sel:DWORD dst_unused:UNUSED_PAD src0_sel:DWORD src1_sel:WORD_1
	global_store_dwordx2 v[82:83], v[10:11], off offset:3072
	global_store_dwordx2 v[84:85], v[12:13], off offset:3072
	global_load_dwordx4 v[10:13], v[78:79], off
	v_mov_b32_e32 v14, v2
	v_mov_b32_e32 v15, v4
	v_mov_b32_e32 v4, v3
	v_mov_b32_e32 v2, v6
	v_mov_b32_e32 v3, v8
	v_mov_b32_e32 v8, v7
	v_pk_mul_f32 v[6:7], v[14:15], v[86:87] op_sel_hi:[1,0]
	v_pk_mul_f32 v[4:5], v[4:5], v[86:87] op_sel_hi:[1,0]
	v_pk_mul_f32 v[2:3], v[2:3], v[88:89] op_sel_hi:[1,0]
	v_pk_mul_f32 v[8:9], v[8:9], v[88:89] op_sel_hi:[1,0]
	s_waitcnt vmcnt(0)
	v_mov_b32_e32 v15, v12
	v_mov_b32_e32 v12, v11
	v_mov_b32_e32 v14, v10
	v_pk_mul_f32 v[4:5], v[4:5], v[12:13]
	v_pk_mul_f32 v[6:7], v[6:7], v[14:15]
	v_pk_mul_f32 v[2:3], v[2:3], v[14:15]
	v_pk_mul_f32 v[8:9], v[8:9], v[12:13]
	v_and_b32_sdwa v12, v5, v92 dst_sel:DWORD dst_unused:UNUSED_PAD src0_sel:WORD_1 src1_sel:DWORD
	v_and_b32_sdwa v13, v4, v92 dst_sel:DWORD dst_unused:UNUSED_PAD src0_sel:WORD_1 src1_sel:DWORD
	v_and_b32_sdwa v10, v7, v92 dst_sel:DWORD dst_unused:UNUSED_PAD src0_sel:WORD_1 src1_sel:DWORD
	v_and_b32_sdwa v11, v6, v92 dst_sel:DWORD dst_unused:UNUSED_PAD src0_sel:WORD_1 src1_sel:DWORD
	v_and_b32_sdwa v14, v3, v92 dst_sel:DWORD dst_unused:UNUSED_PAD src0_sel:WORD_1 src1_sel:DWORD
	v_and_b32_sdwa v15, v2, v92 dst_sel:DWORD dst_unused:UNUSED_PAD src0_sel:WORD_1 src1_sel:DWORD
	v_and_b32_sdwa v16, v9, v92 dst_sel:DWORD dst_unused:UNUSED_PAD src0_sel:WORD_1 src1_sel:DWORD
	v_and_b32_sdwa v17, v8, v92 dst_sel:DWORD dst_unused:UNUSED_PAD src0_sel:WORD_1 src1_sel:DWORD
	v_add3_u32 v5, v5, v12, s5
	v_add3_u32 v4, v4, v13, s5
	v_add3_u32 v6, v6, v11, s5
	v_add3_u32 v7, v7, v10, s5
	v_add3_u32 v10, v2, v15, s5
	v_add3_u32 v11, v3, v14, s5
	v_add3_u32 v2, v9, v16, s5
	v_add3_u32 v3, v8, v17, s5
	v_and_b32_e32 v5, 0xffff0000, v5
	v_and_b32_e32 v4, 0xffff0000, v4
	v_and_b32_e32 v8, 0xffff0000, v2
	v_and_b32_e32 v9, 0xffff0000, v3
	v_or_b32_sdwa v3, v5, v7 dst_sel:DWORD dst_unused:UNUSED_PAD src0_sel:DWORD src1_sel:WORD_1
	v_or_b32_sdwa v2, v4, v6 dst_sel:DWORD dst_unused:UNUSED_PAD src0_sel:DWORD src1_sel:WORD_1
	v_or_b32_sdwa v5, v8, v11 dst_sel:DWORD dst_unused:UNUSED_PAD src0_sel:DWORD src1_sel:WORD_1
	v_or_b32_sdwa v4, v9, v10 dst_sel:DWORD dst_unused:UNUSED_PAD src0_sel:DWORD src1_sel:WORD_1
	global_store_dwordx2 v[82:83], v[2:3], off offset:3584
	global_store_dwordx2 v[84:85], v[4:5], off offset:3584
	s_cbranch_scc0 .LBB0_221
	s_cmp_lt_i32 s99, 0
	s_cbranch_scc1 .LBB0_222
	s_lshr_b32 s10, s99, 9
	s_add_i32 s10, s10, 2
	s_lshl_b32 s10, s10, 12
	s_and_b32 s98, s99, 0x1ff
	s_add_i32 s10, s10, s98
	s_add_i32 s99, s99, 0x600
	s_cmpk_ge_i32 s99, 0xc00
	s_cselect_b32 s99, -1, s99
	s_mov_b32 s98, 0
	s_branch .LBB0_221
